# no per-phase priority flips + one static s_setprio 1 for waves 0-3 at kernel entry
# baseline (speedup 1.0000x reference)
; #define LAS __attribute__((address_space(3)))
; __global__ void __launch_bounds__(NTHR, 2) fwd_megakernel(Args a) {
;     extern __shared__ __attribute__((aligned(16))) unsigned char lds_raw[];
;     LAS unsigned char* lds = (LAS unsigned char*)lds_raw;
;     cg::grid_group grid = cg::this_grid();
;     const int G = gridDim.x, bx = blockIdx.x, lo = a.ph_lo, hi = a.ph_hi;
;     volatile LAS unsigned* bst = (volatile LAS unsigned*)(lds + LDS_BYTES - 16);
;     if (threadIdx.x == 0) { bst[0] = 0u; bst[1] = 0u; }
;     __syncthreads();
;     const XcdBarrier xbar = xcd_barrier_post((unsigned*)(a.ws + WS_BAR), bst);
_Z14fwd_megakernel4Args:
	s_load_dwordx16 s[36:51], s[0:1], 0x80
	s_load_dwordx4 s[68:71], s[0:1], 0xc0
	s_load_dword s3, s[0:1], 0xd0
	s_add_u32 s4, s0, 0xc8
	s_addc_u32 s5, s1, 0
	v_and_b32_e32 v176, 0x3ff, v0
	v_cmp_eq_u32_e64 s[8:9], 0, v176
	s_waitcnt lgkmcnt(0)
	v_readfirstlane_b32 s98, v176
	s_nop 3
	s_lshr_b32 s98, s98, 6
	s_cmp_lt_u32 s98, 4
	s_cbranch_scc0 .Lprio_done
	s_setprio 1
